# FoX attention loop hand-rescheduled: two half-steps per key block (MFMA half with prefetched LDS reads + LDS-DMA issue; softmax half), wave groups g0/g1 staggered by one barrier so softmax overlaps th
# speedup vs baseline: 1.0604x; 1.0390x over previous
.LBB0_544:
	s_and_b64 s[6:7], s[4:5], exec
	v_readfirstlane_b32 s39, v168
	s_cselect_b32 s41, s22, s19
	s_bfe_u32 s40, s39, 0x20006
	s_lshl_b32 s8, s41, 7
	s_lshl_b32 s62, s40, 5
	s_or_b32 s0, s62, s8
	v_or_b32_e32 v160, s0, v166
	v_ashrrev_i32_e32 v161, 31, v160
	v_lshlrev_b64 v[2:3], 8, v[160:161]
	v_lshl_add_u64 v[2:3], v[154:155], 0, v[2:3]
	global_load_dwordx4 v[112:115], v[2:3], off
	global_load_dwordx4 v[116:119], v[2:3], off offset:32
	global_load_dwordx4 v[120:123], v[2:3], off offset:64
	global_load_dwordx4 v[124:127], v[2:3], off offset:96
	global_load_dwordx4 v[128:131], v[2:3], off offset:128
	global_load_dwordx4 v[132:135], v[2:3], off offset:160
	global_load_dwordx4 v[136:139], v[2:3], off offset:192
	global_load_dwordx4 v[140:143], v[2:3], off offset:224
	s_ashr_i32 s9, s8, 31
	s_lshr_b32 s0, s39, 6
	s_lshl_b64 s[6:7], s[8:9], 8
	s_add_u32 s28, s27, s6
	s_addc_u32 s29, s38, s7
	v_lshl_or_b32 v0, s0, 4, v167
	s_add_u32 s30, s23, s6
	v_lshlrev_b32_e32 v2, 8, v0
	s_addc_u32 s31, s24, s7
	s_lshl_b32 s44, s0, 12
	v_or_b32_e32 v163, v2, v171
	v_or_b32_e32 v188, v2, v170
	v_or_b32_e32 v2, 4, v0
	v_bitop3_b32 v3, v0, v168, 4 bitop3:0x36
	s_add_i32 s44, s44, 0
	s_mov_b32 s6, m0
	s_mov_b32 m0, s44
	s_nop 0
	global_load_lds_dwordx4 v163, s[28:29] offset:0
	s_mov_b32 m0, s6
	v_lshlrev_b32_e32 v2, 8, v2
	v_lshlrev_b32_e32 v3, 4, v3
	s_add_i32 s33, s44, 0x8000
	s_mov_b32 s6, m0
	s_mov_b32 m0, s33
	s_nop 0
	global_load_lds_dwordx4 v188, s[30:31] offset:0
	s_mov_b32 m0, s6
	v_and_or_b32 v189, v3, s10, v2
	v_or_b32_e32 v2, 8, v0
	v_bitop3_b32 v3, v0, v168, 8 bitop3:0x36
	s_add_i32 s6, s44, 0x400
	s_mov_b32 s7, m0
	s_mov_b32 m0, s6
	s_nop 0
	global_load_lds_dwordx4 v189, s[28:29] offset:0
	s_mov_b32 m0, s7
	v_lshlrev_b32_e32 v2, 8, v2
	v_lshlrev_b32_e32 v3, 4, v3
	s_mov_b32 s6, m0
	s_mov_b32 m0, s33
	s_nop 0
	global_load_lds_dwordx4 v188, s[30:31] offset:1024
	s_mov_b32 m0, s6
	v_and_or_b32 v190, v3, s10, v2
	v_or_b32_e32 v2, 12, v0
	v_bitop3_b32 v0, v0, v168, 12 bitop3:0x36
	s_add_i32 s6, s44, 0x800
	s_mov_b32 s7, m0
	s_mov_b32 m0, s6
	s_nop 0
	global_load_lds_dwordx4 v190, s[28:29] offset:0
	s_mov_b32 m0, s7
	v_lshlrev_b32_e32 v2, 8, v2
	v_lshlrev_b32_e32 v0, 4, v0
	s_mov_b32 s6, m0
	s_mov_b32 m0, s33
	s_nop 0
	global_load_lds_dwordx4 v188, s[30:31] offset:2048
	s_mov_b32 m0, s6
	v_and_or_b32 v191, v0, s10, v2
	s_add_i32 s6, s44, 0xc00
	s_mov_b32 s7, m0
	s_mov_b32 m0, s6
	s_nop 0
	global_load_lds_dwordx4 v191, s[28:29] offset:0
	s_mov_b32 m0, s7
	s_mov_b32 s28, m0
	s_mov_b32 m0, s33
	s_nop 0
	global_load_lds_dwordx4 v188, s[30:31] offset:3072
	s_mov_b32 m0, s28
	s_lshr_b32 s42, s39, 8
	s_mov_b32 s75, m0
	s_lshl_b32 s73, s0, 12
	s_add_i32 s74, s73, 0x8000
	s_lshl_b32 s72, s42, 8
	s_add_u32 s70, s25, s72
	s_addc_u32 s71, s26, 0
	s_add_i32 s72, s72, 0x10000
	s_cmp_lg_u32 s40, 0
	s_cbranch_scc1 .Lfx_pb0
	s_lshl_b64 s[28:29], s[8:9], 2
	s_add_u32 s28, s70, s28
	s_addc_u32 s29, s71, s29
	s_mov_b32 m0, s72
	s_nop 0
	global_load_lds_dword v172, s[28:29]
.Lfx_pb0:
	s_cmp_lt_i32 s41, 1
	s_cbranch_scc1 .Lfx_pk1
	s_add_i32 s64, s8, 0xffffff80
	s_ashr_i32 s65, s64, 31
	s_lshl_b64 s[66:67], s[64:65], 8
	s_add_u32 s28, s27, s66
	s_addc_u32 s29, s38, s67
	s_add_i32 s33, s73, 0x10200
	s_mov_b32 m0, s33
	s_nop 0
	global_load_lds_dwordx4 v163, s[28:29]
	s_add_i32 m0, s33, 0x400
	s_nop 0
	global_load_lds_dwordx4 v189, s[28:29]
	s_add_i32 m0, s33, 0x800
	s_nop 0
	global_load_lds_dwordx4 v190, s[28:29]
	s_add_i32 m0, s33, 0xc00
	s_nop 0
	global_load_lds_dwordx4 v191, s[28:29]
	s_cmp_lg_u32 s40, 0
	s_cbranch_scc1 .Lfx_pk1
	s_lshl_b64 s[66:67], s[64:65], 2
	s_add_u32 s28, s70, s66
	s_addc_u32 s29, s71, s67
	s_add_i32 m0, s72, 0x10200
	s_nop 0
	global_load_lds_dword v172, s[28:29]
.Lfx_pk1:
	s_waitcnt vmcnt(0) lgkmcnt(0)
	s_barrier
	s_cmp_lt_i32 s41, 0
	s_cbranch_scc1 .LBB0_560
	v_mov_b64_e32 v[16:17], 0
	v_mov_b64_e32 v[18:19], 0
	v_mov_b64_e32 v[20:21], 0
	v_mov_b64_e32 v[22:23], 0
	v_mov_b64_e32 v[24:25], 0
	v_mov_b64_e32 v[26:27], 0
	v_mov_b64_e32 v[28:29], 0
	v_mov_b64_e32 v[30:31], 0
	v_mov_b64_e32 v[32:33], 0
	v_mov_b64_e32 v[34:35], 0
	v_mov_b64_e32 v[36:37], 0
	v_mov_b64_e32 v[38:39], 0
	v_mov_b64_e32 v[40:41], 0
	v_mov_b64_e32 v[42:43], 0
	v_mov_b64_e32 v[44:45], 0
	v_mov_b64_e32 v[46:47], 0
	v_mov_b64_e32 v[48:49], 0
	v_mov_b64_e32 v[50:51], 0
	v_mov_b64_e32 v[52:53], 0
	v_mov_b64_e32 v[54:55], 0
	v_mov_b64_e32 v[56:57], 0
	v_mov_b64_e32 v[58:59], 0
	v_mov_b64_e32 v[60:61], 0
	v_mov_b64_e32 v[62:63], 0
	v_mov_b64_e32 v[64:65], 0
	v_mov_b64_e32 v[66:67], 0
	v_mov_b64_e32 v[68:69], 0
	v_mov_b64_e32 v[70:71], 0
	v_mov_b64_e32 v[72:73], 0
	v_mov_b64_e32 v[74:75], 0
	v_mov_b64_e32 v[76:77], 0
	v_mov_b64_e32 v[78:79], 0
	v_mov_b32_e32 v192, 0xe0ad78ec
	v_mov_b32_e32 v162, 0
	s_lshl_b32 s50, s42, 6
	s_lshl_b32 s51, s42, 14
	s_sub_i32 s62, s62, s50
	s_add_i32 s62, s62, 30
	s_mov_b32 s63, 0
	s_mov_b32 s76, 0
	s_mov_b32 s77, 0x10200
	s_mov_b64 s[80:81], 0
	s_cmp_eq_u32 s42, 0
	s_cbranch_scc1 .Lfx_body
	s_barrier
.Lfx_body:
	s_cmp_lt_u32 s62, 0x4000005e
	s_cselect_b64 s[78:79], -1, 0
	s_andn2_b64 vcc, exec, s[78:79]
	s_cbranch_vccnz .Lfx_h1_done
	s_andn2_b64 vcc, exec, s[80:81]
	s_cbranch_vccnz .Lfx_h1_qonly
	s_lshl_b32 s64, s41, 7
	s_mov_b32 s66, s64
	s_ashr_i32 s67, s64, 31
	s_lshl_b64 s[30:31], s[66:67], 8
	s_add_u32 s30, s23, s30
	s_addc_u32 s31, s24, s31
	s_add_i32 s66, s64, 0xffffff80
	s_ashr_i32 s67, s66, 31
	s_lshl_b64 s[28:29], s[66:67], 8
	s_add_u32 s28, s27, s28
	s_addc_u32 s29, s38, s29
	s_lshl_b64 s[68:69], s[66:67], 2
	s_add_u32 s68, s70, s68
	s_addc_u32 s69, s71, s69
	s_cmp_gt_u32 s63, 0
	s_cselect_b32 s82, 1, 0
	s_cmp_gt_i32 s41, 0
	s_cselect_b32 s84, s82, 0
	s_cmp_eq_u32 s40, 0
	s_cselect_b32 s86, s84, 0
	s_add_i32 s64, s77, s51
	v_add_u32_e32 v10, s64, v183
	v_add_u32_e32 v11, s64, v184
	v_add_u32_e32 v12, s64, v185
	v_add_u32_e32 v13, s64, v186
	s_add_i32 s65, s76, s51
	v_add_u32_e32 v14, s65, v174
	s_lshl_b32 s66, s50, 2
	s_add_i32 s66, s66, s76
	v_lshl_add_u32 v0, v144, 2, s66
	v_add_u32_e32 v0, 0x10000, v0
	ds_read_b64_tr_b16 v[2:3], v10 offset:32768
	ds_read_b64_tr_b16 v[4:5], v10 offset:34816
	ds_read_b64_tr_b16 v[6:7], v10 offset:36864
	ds_read_b64_tr_b16 v[8:9], v10 offset:38912
	ds_read_b64_tr_b16 v[212:213], v10 offset:40960
	ds_read_b64_tr_b16 v[214:215], v10 offset:43008
	ds_read_b64_tr_b16 v[216:217], v10 offset:45056
	ds_read_b64_tr_b16 v[218:219], v10 offset:47104
	s_waitcnt lgkmcnt(6)
	v_mfma_f32_32x32x16_bf16 v[64:79], v[2:5], v[196:199], v[64:79]
	ds_read_b64_tr_b16 v[220:221], v11 offset:32768
	ds_read_b64_tr_b16 v[222:223], v11 offset:34816
	ds_read_b128 v[96:99], v0
	s_waitcnt lgkmcnt(7)
	v_mfma_f32_32x32x16_bf16 v[64:79], v[6:9], v[204:207], v[64:79]
	ds_read_b64_tr_b16 v[224:225], v11 offset:36864
	ds_read_b64_tr_b16 v[226:227], v11 offset:38912
	s_cmp_eq_u32 s82, 0
	s_cbranch_scc1 .Lfx_dm1_pq
	s_add_i32 m0, s74, s76
	s_nop 0
	global_load_lds_dwordx4 v188, s[30:31]
.Lfx_dm1_pq:
	ds_read_b128 v[100:103], v0 offset:32
	s_waitcnt lgkmcnt(8)
	v_mfma_f32_32x32x16_bf16 v[64:79], v[212:215], v[200:203], v[64:79]
	ds_read_b64_tr_b16 v[228:229], v11 offset:40960
	ds_read_b64_tr_b16 v[230:231], v11 offset:43008
	ds_read_b128 v[80:83], v0 offset:128
	s_waitcnt lgkmcnt(9)
	v_mfma_f32_32x32x16_bf16 v[64:79], v[216:219], v[208:211], v[64:79]
	ds_read_b64_tr_b16 v[232:233], v11 offset:45056
	ds_read_b64_tr_b16 v[234:235], v11 offset:47104
	ds_read_b128 v[84:87], v0 offset:160
	s_waitcnt lgkmcnt(10)
	v_mfma_f32_32x32x16_bf16 v[48:63], v[220:223], v[196:199], v[48:63]
	ds_read_b64_tr_b16 v[2:3], v12 offset:32768
	ds_read_b64_tr_b16 v[4:5], v12 offset:34816
	s_cmp_eq_u32 s82, 0
	s_cbranch_scc1 .Lfx_dm2_pq
	s_nop 0
	global_load_lds_dwordx4 v188, s[30:31] offset:1024
.Lfx_dm2_pq:
	ds_read_b128 v[104:107], v0 offset:64
	s_waitcnt lgkmcnt(10)
	v_mfma_f32_32x32x16_bf16 v[48:63], v[224:227], v[204:207], v[48:63]
	ds_read_b64_tr_b16 v[6:7], v12 offset:36864
	ds_read_b64_tr_b16 v[8:9], v12 offset:38912
	ds_read_b128 v[108:111], v0 offset:96
	s_waitcnt lgkmcnt(10)
	v_mfma_f32_32x32x16_bf16 v[48:63], v[228:231], v[200:203], v[48:63]
	ds_read_b64_tr_b16 v[212:213], v12 offset:40960
	ds_read_b64_tr_b16 v[214:215], v12 offset:43008
	ds_read_b128 v[88:91], v0 offset:192
	s_waitcnt lgkmcnt(10)
	v_mfma_f32_32x32x16_bf16 v[48:63], v[232:235], v[208:211], v[48:63]
	ds_read_b64_tr_b16 v[216:217], v12 offset:45056
	ds_read_b64_tr_b16 v[218:219], v12 offset:47104
	s_cmp_eq_u32 s82, 0
	s_cbranch_scc1 .Lfx_dm3_pq
	s_nop 0
	global_load_lds_dwordx4 v188, s[30:31] offset:2048
.Lfx_dm3_pq:
	ds_read_b128 v[92:95], v0 offset:224
	s_waitcnt lgkmcnt(10)
	v_mfma_f32_32x32x16_bf16 v[32:47], v[2:5], v[196:199], v[32:47]
	ds_read_b64_tr_b16 v[220:221], v13 offset:32768
	ds_read_b64_tr_b16 v[222:223], v13 offset:34816
	s_waitcnt lgkmcnt(9)
	v_mfma_f32_32x32x16_bf16 v[32:47], v[6:9], v[204:207], v[32:47]
	ds_read_b64_tr_b16 v[224:225], v13 offset:36864
	ds_read_b64_tr_b16 v[226:227], v13 offset:38912
	s_waitcnt lgkmcnt(8)
	v_mfma_f32_32x32x16_bf16 v[32:47], v[212:215], v[200:203], v[32:47]
	ds_read_b64_tr_b16 v[228:229], v13 offset:40960
	ds_read_b64_tr_b16 v[230:231], v13 offset:43008
	s_cmp_eq_u32 s82, 0
	s_cbranch_scc1 .Lfx_dm4_pq
	s_nop 0
	global_load_lds_dwordx4 v188, s[30:31] offset:3072
.Lfx_dm4_pq:
	s_waitcnt lgkmcnt(7)
	v_mfma_f32_32x32x16_bf16 v[32:47], v[216:219], v[208:211], v[32:47]
	ds_read_b64_tr_b16 v[232:233], v13 offset:45056
	ds_read_b64_tr_b16 v[234:235], v13 offset:47104
	s_waitcnt lgkmcnt(6)
	v_mfma_f32_32x32x16_bf16 v[16:31], v[220:223], v[196:199], v[16:31]
	v_add_u32_e32 v15, v14, v175
	ds_read_b128 v[2:5], v15
	s_waitcnt lgkmcnt(5)
	v_mfma_f32_32x32x16_bf16 v[16:31], v[224:227], v[204:207], v[16:31]
	ds_read_b128 v[6:9], v15 offset:8192
	s_cmp_eq_u32 s84, 0
	s_cbranch_scc1 .Lfx_dm5_pq
	s_add_i32 s33, s73, s77
	s_mov_b32 m0, s33
	s_nop 0
	global_load_lds_dwordx4 v163, s[28:29]
.Lfx_dm5_pq:
	s_waitcnt lgkmcnt(4)
	v_mfma_f32_32x32x16_bf16 v[16:31], v[228:231], v[200:203], v[16:31]
	v_add_u32_e32 v15, v14, v176
	ds_read_b128 v[212:215], v15
	s_waitcnt lgkmcnt(3)
	v_mfma_f32_32x32x16_bf16 v[16:31], v[232:235], v[208:211], v[16:31]
	ds_read_b128 v[216:219], v15 offset:8192
	s_waitcnt lgkmcnt(3)
	v_mfma_f32_32x32x16_bf16 v[96:111], v[2:5], v[112:115], v[96:111]
	v_add_u32_e32 v15, v14, v177
	ds_read_b128 v[220:223], v15
	s_cmp_eq_u32 s84, 0
	s_cbranch_scc1 .Lfx_dm6_pq
	s_add_i32 m0, s33, 0x400
	s_nop 0
	global_load_lds_dwordx4 v189, s[28:29]
.Lfx_dm6_pq:
	s_waitcnt lgkmcnt(3)
	v_mfma_f32_32x32x16_bf16 v[80:95], v[6:9], v[112:115], v[80:95]
	ds_read_b128 v[224:227], v15 offset:8192
	s_waitcnt lgkmcnt(3)
	v_mfma_f32_32x32x16_bf16 v[96:111], v[212:215], v[116:119], v[96:111]
	v_add_u32_e32 v15, v14, v178
	ds_read_b128 v[228:231], v15
	s_waitcnt lgkmcnt(3)
	v_mfma_f32_32x32x16_bf16 v[80:95], v[216:219], v[116:119], v[80:95]
	ds_read_b128 v[232:235], v15 offset:8192
	s_cmp_eq_u32 s84, 0
	s_cbranch_scc1 .Lfx_dm7_pq
	s_add_i32 m0, s33, 0x800
	s_nop 0
	global_load_lds_dwordx4 v190, s[28:29]
.Lfx_dm7_pq:
	s_waitcnt lgkmcnt(3)
	v_mfma_f32_32x32x16_bf16 v[96:111], v[220:223], v[120:123], v[96:111]
	v_add_u32_e32 v15, v14, v179
	ds_read_b128 v[2:5], v15
	s_waitcnt lgkmcnt(3)
	v_mfma_f32_32x32x16_bf16 v[80:95], v[224:227], v[120:123], v[80:95]
	ds_read_b128 v[6:9], v15 offset:8192
	s_waitcnt lgkmcnt(3)
	v_mfma_f32_32x32x16_bf16 v[96:111], v[228:231], v[124:127], v[96:111]
	v_add_u32_e32 v15, v14, v180
	ds_read_b128 v[212:215], v15
	s_cmp_eq_u32 s84, 0
	s_cbranch_scc1 .Lfx_dm8_pq
	s_add_i32 m0, s33, 0xc00
	s_nop 0
	global_load_lds_dwordx4 v191, s[28:29]
.Lfx_dm8_pq:
	s_waitcnt lgkmcnt(3)
	v_mfma_f32_32x32x16_bf16 v[80:95], v[232:235], v[124:127], v[80:95]
	ds_read_b128 v[216:219], v15 offset:8192
	s_waitcnt lgkmcnt(3)
	v_mfma_f32_32x32x16_bf16 v[96:111], v[2:5], v[128:131], v[96:111]
	v_add_u32_e32 v15, v14, v181
	ds_read_b128 v[220:223], v15
	s_waitcnt lgkmcnt(3)
	v_mfma_f32_32x32x16_bf16 v[80:95], v[6:9], v[128:131], v[80:95]
	ds_read_b128 v[224:227], v15 offset:8192
	s_cmp_eq_u32 s86, 0
	s_cbranch_scc1 .Lfx_dm9_pq
	s_add_i32 m0, s72, s77
	s_nop 0
	global_load_lds_dword v172, s[68:69]
.Lfx_dm9_pq:
	s_waitcnt lgkmcnt(3)
	v_mfma_f32_32x32x16_bf16 v[96:111], v[212:215], v[132:135], v[96:111]
	v_add_u32_e32 v15, v14, v182
	ds_read_b128 v[228:231], v15
	s_waitcnt lgkmcnt(3)
	v_mfma_f32_32x32x16_bf16 v[80:95], v[216:219], v[132:135], v[80:95]
	ds_read_b128 v[232:235], v15 offset:8192
	s_waitcnt lgkmcnt(3)
	v_mfma_f32_32x32x16_bf16 v[96:111], v[220:223], v[136:139], v[96:111]
	s_waitcnt lgkmcnt(2)
	v_mfma_f32_32x32x16_bf16 v[80:95], v[224:227], v[136:139], v[80:95]
	s_waitcnt lgkmcnt(1)
	v_mfma_f32_32x32x16_bf16 v[96:111], v[228:231], v[140:143], v[96:111]
	s_waitcnt lgkmcnt(0)
	v_mfma_f32_32x32x16_bf16 v[80:95], v[232:235], v[140:143], v[80:95]
	s_nop 7
	s_branch .Lfx_h1_done
.Lfx_h1_qonly:
	s_lshl_b32 s64, s41, 7
	s_mov_b32 s66, s64
	s_ashr_i32 s67, s64, 31
	s_lshl_b64 s[30:31], s[66:67], 8
	s_add_u32 s30, s23, s30
	s_addc_u32 s31, s24, s31
	s_add_i32 s66, s64, 0xffffff80
	s_ashr_i32 s67, s66, 31
	s_lshl_b64 s[28:29], s[66:67], 8
	s_add_u32 s28, s27, s28
	s_addc_u32 s29, s38, s29
	s_lshl_b64 s[68:69], s[66:67], 2
	s_add_u32 s68, s70, s68
	s_addc_u32 s69, s71, s69
	s_cmp_gt_u32 s63, 0
	s_cselect_b32 s82, 1, 0
	s_cmp_gt_i32 s41, 0
	s_cselect_b32 s84, s82, 0
	s_cmp_eq_u32 s40, 0
	s_cselect_b32 s86, s84, 0
	s_add_i32 s65, s76, s51
	v_add_u32_e32 v14, s65, v174
	s_lshl_b32 s66, s50, 2
	s_add_i32 s66, s66, s76
	v_lshl_add_u32 v0, v144, 2, s66
	v_add_u32_e32 v0, 0x10000, v0
	ds_read_b128 v[96:99], v0
	ds_read_b128 v[100:103], v0 offset:32
	ds_read_b128 v[80:83], v0 offset:128
	ds_read_b128 v[84:87], v0 offset:160
	ds_read_b128 v[104:107], v0 offset:64
	ds_read_b128 v[108:111], v0 offset:96
	ds_read_b128 v[88:91], v0 offset:192
	ds_read_b128 v[92:95], v0 offset:224
	v_add_u32_e32 v15, v14, v175
	ds_read_b128 v[2:5], v15
	ds_read_b128 v[6:9], v15 offset:8192
	v_add_u32_e32 v15, v14, v176
	ds_read_b128 v[212:215], v15
	ds_read_b128 v[216:219], v15 offset:8192
	s_waitcnt lgkmcnt(3)
	v_mfma_f32_32x32x16_bf16 v[96:111], v[2:5], v[112:115], v[96:111]
	v_add_u32_e32 v15, v14, v177
	ds_read_b128 v[220:223], v15
	s_waitcnt lgkmcnt(3)
	v_mfma_f32_32x32x16_bf16 v[80:95], v[6:9], v[112:115], v[80:95]
	ds_read_b128 v[224:227], v15 offset:8192
	s_cmp_eq_u32 s82, 0
	s_cbranch_scc1 .Lfx_dm10_q
	s_add_i32 m0, s74, s76
	s_nop 0
	global_load_lds_dwordx4 v188, s[30:31]
.Lfx_dm10_q:
	s_waitcnt lgkmcnt(3)
	v_mfma_f32_32x32x16_bf16 v[96:111], v[212:215], v[116:119], v[96:111]
	v_add_u32_e32 v15, v14, v178
	ds_read_b128 v[228:231], v15
	s_waitcnt lgkmcnt(3)
	v_mfma_f32_32x32x16_bf16 v[80:95], v[216:219], v[116:119], v[80:95]
	ds_read_b128 v[232:235], v15 offset:8192
	s_waitcnt lgkmcnt(3)
	v_mfma_f32_32x32x16_bf16 v[96:111], v[220:223], v[120:123], v[96:111]
	v_add_u32_e32 v15, v14, v179
	ds_read_b128 v[2:5], v15
	s_cmp_eq_u32 s82, 0
	s_cbranch_scc1 .Lfx_dm11_q
	s_nop 0
	global_load_lds_dwordx4 v188, s[30:31] offset:1024
.Lfx_dm11_q:
	s_waitcnt lgkmcnt(3)
	v_mfma_f32_32x32x16_bf16 v[80:95], v[224:227], v[120:123], v[80:95]
	ds_read_b128 v[6:9], v15 offset:8192
	s_waitcnt lgkmcnt(3)
	v_mfma_f32_32x32x16_bf16 v[96:111], v[228:231], v[124:127], v[96:111]
	v_add_u32_e32 v15, v14, v180
	ds_read_b128 v[212:215], v15
	s_waitcnt lgkmcnt(3)
	v_mfma_f32_32x32x16_bf16 v[80:95], v[232:235], v[124:127], v[80:95]
	ds_read_b128 v[216:219], v15 offset:8192
	s_cmp_eq_u32 s82, 0
	s_cbranch_scc1 .Lfx_dm12_q
	s_nop 0
	global_load_lds_dwordx4 v188, s[30:31] offset:2048
.Lfx_dm12_q:
	s_waitcnt lgkmcnt(3)
	v_mfma_f32_32x32x16_bf16 v[96:111], v[2:5], v[128:131], v[96:111]
	v_add_u32_e32 v15, v14, v181
	ds_read_b128 v[220:223], v15
	s_waitcnt lgkmcnt(3)
	v_mfma_f32_32x32x16_bf16 v[80:95], v[6:9], v[128:131], v[80:95]
	ds_read_b128 v[224:227], v15 offset:8192
	s_waitcnt lgkmcnt(3)
	v_mfma_f32_32x32x16_bf16 v[96:111], v[212:215], v[132:135], v[96:111]
	v_add_u32_e32 v15, v14, v182
	ds_read_b128 v[228:231], v15
	s_cmp_eq_u32 s82, 0
	s_cbranch_scc1 .Lfx_dm13_q
	s_nop 0
	global_load_lds_dwordx4 v188, s[30:31] offset:3072
.Lfx_dm13_q:
	s_waitcnt lgkmcnt(3)
	v_mfma_f32_32x32x16_bf16 v[80:95], v[216:219], v[132:135], v[80:95]
	ds_read_b128 v[232:235], v15 offset:8192
	s_waitcnt lgkmcnt(3)
	v_mfma_f32_32x32x16_bf16 v[96:111], v[220:223], v[136:139], v[96:111]
	s_waitcnt lgkmcnt(2)
	v_mfma_f32_32x32x16_bf16 v[80:95], v[224:227], v[136:139], v[80:95]
	s_cmp_eq_u32 s84, 0
	s_cbranch_scc1 .Lfx_dm14_q
	s_add_i32 s33, s73, s77
	s_mov_b32 m0, s33
	s_nop 0
	global_load_lds_dwordx4 v163, s[28:29]
.Lfx_dm14_q:
	s_waitcnt lgkmcnt(1)
	v_mfma_f32_32x32x16_bf16 v[96:111], v[228:231], v[140:143], v[96:111]
	s_waitcnt lgkmcnt(0)
	v_mfma_f32_32x32x16_bf16 v[80:95], v[232:235], v[140:143], v[80:95]
	s_cmp_eq_u32 s84, 0
	s_cbranch_scc1 .Lfx_dm15_q
	s_add_i32 m0, s33, 0x400
	s_nop 0
	global_load_lds_dwordx4 v189, s[28:29]
.Lfx_dm15_q:
	s_cmp_eq_u32 s84, 0
	s_cbranch_scc1 .Lfx_dm16_q
	s_add_i32 m0, s33, 0x800
	s_nop 0
	global_load_lds_dwordx4 v190, s[28:29]
.Lfx_dm16_q:
	s_cmp_eq_u32 s84, 0
	s_cbranch_scc1 .Lfx_dm17_q
	s_add_i32 m0, s33, 0xc00
	s_nop 0
	global_load_lds_dwordx4 v191, s[28:29]
.Lfx_dm17_q:
	s_cmp_eq_u32 s86, 0
	s_cbranch_scc1 .Lfx_dm18_q
	s_add_i32 m0, s72, s77
	s_nop 0
	global_load_lds_dword v172, s[68:69]
.Lfx_dm18_q:
	s_add_i32 s29, s62, 0xc0000001
	s_cmp_gt_u32 s29, 0xc000005d
	s_cbranch_scc1 .Lfx_nomask_q
	s_nop 11
	v_add_u32_e32 v0, s62, v147
	v_subrev_u32_e32 v2, 30, v0
	v_cmp_gt_u32_e32 vcc, 2.0, v2
	v_add_u32_e32 v2, 0xbfffffc2, v0
	s_nop 3
	v_cndmask_b32_e32 v96, v187, v96, vcc
	v_cmp_lt_u32_e32 vcc, s17, v2
	v_subrev_u32_e32 v2, 31, v0
	s_nop 0
	v_cndmask_b32_e32 v80, v187, v80, vcc
	v_cmp_gt_u32_e32 vcc, 2.0, v2
	v_add_u32_e32 v2, 0xbfffffc1, v0
	s_nop 0
	v_cndmask_b32_e32 v97, v187, v97, vcc
	v_cmp_lt_u32_e32 vcc, s17, v2
	v_subrev_u32_e32 v2, 32, v0
	s_nop 0
	v_cndmask_b32_e32 v81, v187, v81, vcc
	v_cmp_gt_u32_e32 vcc, 2.0, v2
	v_add_u32_e32 v2, 0xbfffffc0, v0
	s_nop 0
	v_cndmask_b32_e32 v98, v187, v98, vcc
	v_cmp_lt_u32_e32 vcc, s17, v2
	v_subrev_u32_e32 v2, 33, v0
	s_nop 0
	v_cndmask_b32_e32 v82, v187, v82, vcc
	v_cmp_gt_u32_e32 vcc, 2.0, v2
	v_add_u32_e32 v2, 0xbfffffbf, v0
	s_nop 0
	v_cndmask_b32_e32 v99, v187, v99, vcc
	v_cmp_lt_u32_e32 vcc, s17, v2
	v_subrev_u32_e32 v2, 38, v0
	s_nop 0
	v_cndmask_b32_e32 v83, v187, v83, vcc
	v_cmp_gt_u32_e32 vcc, 2.0, v2
	v_add_u32_e32 v2, 0xbfffffba, v0
	s_nop 0
	v_cndmask_b32_e32 v100, v187, v100, vcc
	v_cmp_lt_u32_e32 vcc, s17, v2
	v_subrev_u32_e32 v2, 39, v0
	s_nop 0
	v_cndmask_b32_e32 v84, v187, v84, vcc
	v_cmp_gt_u32_e32 vcc, 2.0, v2
	v_add_u32_e32 v2, 0xbfffffb9, v0
	s_nop 0
	v_cndmask_b32_e32 v101, v187, v101, vcc
	v_cmp_lt_u32_e32 vcc, s17, v2
	v_subrev_u32_e32 v2, 40, v0
	s_nop 0
	v_cndmask_b32_e32 v85, v187, v85, vcc
	v_cmp_gt_u32_e32 vcc, 2.0, v2
	v_add_u32_e32 v2, 0xbfffffb8, v0
	s_nop 0
	v_cndmask_b32_e32 v102, v187, v102, vcc
	v_cmp_lt_u32_e32 vcc, s17, v2
	v_subrev_u32_e32 v2, 41, v0
	s_nop 0
	v_cndmask_b32_e32 v86, v187, v86, vcc
	v_cmp_gt_u32_e32 vcc, 2.0, v2
	v_add_u32_e32 v2, 0xbfffffb7, v0
	s_nop 0
	v_cndmask_b32_e32 v103, v187, v103, vcc
	v_cmp_lt_u32_e32 vcc, s17, v2
	v_subrev_u32_e32 v2, 46, v0
	s_nop 0
	v_cndmask_b32_e32 v87, v187, v87, vcc
	v_cmp_gt_u32_e32 vcc, 2.0, v2
	v_add_u32_e32 v2, 0xbfffffb2, v0
	s_nop 0
	v_cndmask_b32_e32 v104, v187, v104, vcc
	v_cmp_lt_u32_e32 vcc, s17, v2
	v_subrev_u32_e32 v2, 47, v0
	s_nop 0
	v_cndmask_b32_e32 v88, v187, v88, vcc
	v_cmp_gt_u32_e32 vcc, 2.0, v2
	v_add_u32_e32 v2, 0xbfffffb1, v0
	s_nop 0
	v_cndmask_b32_e32 v105, v187, v105, vcc
	v_cmp_lt_u32_e32 vcc, s17, v2
	v_subrev_u32_e32 v2, 48, v0
	s_nop 0
	v_cndmask_b32_e32 v89, v187, v89, vcc
	v_cmp_gt_u32_e32 vcc, 2.0, v2
	v_add_u32_e32 v2, 0xbfffffb0, v0
	s_nop 0
	v_cndmask_b32_e32 v106, v187, v106, vcc
	v_cmp_lt_u32_e32 vcc, s17, v2
	v_subrev_u32_e32 v2, 49, v0
	s_nop 0
	v_cndmask_b32_e32 v90, v187, v90, vcc
	v_cmp_gt_u32_e32 vcc, 2.0, v2
	v_add_u32_e32 v2, 0xbfffffaf, v0
	s_nop 0
	v_cndmask_b32_e32 v107, v187, v107, vcc
	v_cmp_lt_u32_e32 vcc, s17, v2
	v_subrev_u32_e32 v2, 54, v0
	s_nop 0
	v_cndmask_b32_e32 v91, v187, v91, vcc
	v_cmp_gt_u32_e32 vcc, 2.0, v2
	v_add_u32_e32 v2, 0xbfffffaa, v0
	s_nop 0
	v_cndmask_b32_e32 v108, v187, v108, vcc
	v_cmp_lt_u32_e32 vcc, s17, v2
	v_subrev_u32_e32 v2, 55, v0
	s_nop 0
	v_cndmask_b32_e32 v92, v187, v92, vcc
	v_cmp_gt_u32_e32 vcc, 2.0, v2
	v_add_u32_e32 v2, 0xbfffffa9, v0
	s_nop 0
	v_cndmask_b32_e32 v109, v187, v109, vcc
	v_cmp_lt_u32_e32 vcc, s17, v2
	v_subrev_u32_e32 v2, 56, v0
	s_nop 0
	v_cndmask_b32_e32 v93, v187, v93, vcc
	v_cmp_gt_u32_e32 vcc, 2.0, v2
	v_add_u32_e32 v2, 0xbfffffa8, v0
	s_nop 0
	v_cndmask_b32_e32 v110, v187, v110, vcc
	v_cmp_lt_u32_e32 vcc, s17, v2
	v_subrev_u32_e32 v2, 57, v0
	v_add_u32_e32 v0, 0xbfffffa7, v0
	v_cndmask_b32_e32 v94, v187, v94, vcc
	v_cmp_gt_u32_e32 vcc, 2.0, v2
	s_nop 1
	v_cndmask_b32_e32 v111, v187, v111, vcc
	v_cmp_lt_u32_e32 vcc, s17, v0
	s_nop 1
	v_cndmask_b32_e32 v95, v187, v95, vcc
.Lfx_nomask_q:
	s_nop 7
.Lfx_h1_done:
	s_barrier
	s_andn2_b64 vcc, exec, s[78:79]
	s_cbranch_vccnz .Lfx_h2_invis
	s_nop 3
	v_max3_f32 v0, v96, v97, v80
	v_max3_f32 v2, v98, v99, v81
	v_max3_f32 v0, v0, v82, v83
	v_max3_f32 v2, v2, v102, v103
	v_max3_f32 v0, v0, v100, v101
	v_max3_f32 v2, v2, v86, v87
	v_max3_f32 v0, v0, v84, v85
	v_max3_f32 v2, v2, v106, v107
	v_max3_f32 v0, v0, v104, v105
	v_max3_f32 v2, v2, v90, v91
	v_max3_f32 v0, v0, v88, v89
	v_max3_f32 v2, v2, v110, v111
	v_max3_f32 v0, v0, v108, v109
	v_max3_f32 v2, v2, v94, v95
	v_max3_f32 v0, v0, v92, v93
	v_max_f32_e32 v2, v2, v2
	v_max_f32_e32 v0, v0, v0
	v_max_f32_e32 v0, v0, v2
	v_mov_b32_e32 v2, v0
	s_nop 1
	v_permlane32_swap_b32_e32 v0, v2
	v_max_f32_e32 v2, v2, v2
	v_max_f32_e32 v0, v0, v0
	v_max_f32_e32 v0, v0, v2
	v_add_f32_e32 v2, 0x41000000, v192
	v_cmp_gt_f32_e32 vcc, v0, v2
	s_cbranch_vccz .Lfx_sm_exp_v
	v_max_f32_e32 v0, v0, v0
	v_max_f32_e32 v2, v192, v192
	v_max_f32_e32 v2, v2, v0
	v_sub_f32_e32 v0, v192, v2
	v_exp_f32_e32 v0, v0
	v_mov_b32_e32 v192, v2
	v_mul_f32_e32 v162, v162, v0
	v_pk_mul_f32 v[78:79], v[78:79], v[0:1] op_sel_hi:[1,0]
	v_pk_mul_f32 v[76:77], v[76:77], v[0:1] op_sel_hi:[1,0]
	v_pk_mul_f32 v[74:75], v[74:75], v[0:1] op_sel_hi:[1,0]
	v_pk_mul_f32 v[72:73], v[72:73], v[0:1] op_sel_hi:[1,0]
	v_pk_mul_f32 v[70:71], v[70:71], v[0:1] op_sel_hi:[1,0]
	v_pk_mul_f32 v[68:69], v[68:69], v[0:1] op_sel_hi:[1,0]
	v_pk_mul_f32 v[66:67], v[66:67], v[0:1] op_sel_hi:[1,0]
	v_pk_mul_f32 v[64:65], v[64:65], v[0:1] op_sel_hi:[1,0]
	v_pk_mul_f32 v[62:63], v[62:63], v[0:1] op_sel_hi:[1,0]
	v_pk_mul_f32 v[60:61], v[60:61], v[0:1] op_sel_hi:[1,0]
	v_pk_mul_f32 v[58:59], v[58:59], v[0:1] op_sel_hi:[1,0]
	v_pk_mul_f32 v[56:57], v[56:57], v[0:1] op_sel_hi:[1,0]
	v_pk_mul_f32 v[54:55], v[54:55], v[0:1] op_sel_hi:[1,0]
	v_pk_mul_f32 v[52:53], v[52:53], v[0:1] op_sel_hi:[1,0]
	v_pk_mul_f32 v[50:51], v[50:51], v[0:1] op_sel_hi:[1,0]
	v_pk_mul_f32 v[48:49], v[48:49], v[0:1] op_sel_hi:[1,0]
	v_pk_mul_f32 v[46:47], v[46:47], v[0:1] op_sel_hi:[1,0]
	v_pk_mul_f32 v[44:45], v[44:45], v[0:1] op_sel_hi:[1,0]
	v_pk_mul_f32 v[42:43], v[42:43], v[0:1] op_sel_hi:[1,0]
	v_pk_mul_f32 v[40:41], v[40:41], v[0:1] op_sel_hi:[1,0]
	v_pk_mul_f32 v[38:39], v[38:39], v[0:1] op_sel_hi:[1,0]
	v_pk_mul_f32 v[36:37], v[36:37], v[0:1] op_sel_hi:[1,0]
	v_pk_mul_f32 v[34:35], v[34:35], v[0:1] op_sel_hi:[1,0]
	v_pk_mul_f32 v[32:33], v[32:33], v[0:1] op_sel_hi:[1,0]
	v_pk_mul_f32 v[30:31], v[30:31], v[0:1] op_sel_hi:[1,0]
	v_pk_mul_f32 v[28:29], v[28:29], v[0:1] op_sel_hi:[1,0]
	v_pk_mul_f32 v[26:27], v[26:27], v[0:1] op_sel_hi:[1,0]
	v_pk_mul_f32 v[24:25], v[24:25], v[0:1] op_sel_hi:[1,0]
	v_pk_mul_f32 v[22:23], v[22:23], v[0:1] op_sel_hi:[1,0]
	v_pk_mul_f32 v[20:21], v[20:21], v[0:1] op_sel_hi:[1,0]
	v_pk_mul_f32 v[18:19], v[18:19], v[0:1] op_sel_hi:[1,0]
	v_pk_mul_f32 v[16:17], v[16:17], v[0:1] op_sel_hi:[1,0]
.Lfx_sm_exp_v:
	v_sub_f32_e32 v0, v96, v192
	v_exp_f32_e32 v193, v0
	v_sub_f32_e32 v0, v80, v192
	v_exp_f32_e32 v194, v0
	v_sub_f32_e32 v0, v97, v192
	v_exp_f32_e32 v2, v0
	v_sub_f32_e32 v0, v81, v192
	v_exp_f32_e32 v0, v0
	v_add_f32_e32 v3, v193, v194
	v_add_f32_e32 v4, v2, v0
	v_add_f32_e32 v5, v3, v1
	s_nop 0
	v_add_f32_e32 v8, v4, v4
	v_add_f32_e32 v9, v4, v5
	v_sub_f32_e32 v3, v98, v192
	v_sub_f32_e32 v4, v82, v192
	v_exp_f32_e32 v3, v3
	v_exp_f32_e32 v98, v4
	v_sub_f32_e32 v4, v99, v192
	v_sub_f32_e32 v5, v83, v192
	v_exp_f32_e32 v4, v4
	v_exp_f32_e32 v8, v5
	v_add_f32_e32 v5, v3, v98
	v_cvt_pk_bf16_f32 v196, v193, v2
	v_cvt_pk_bf16_f32 v197, v3, v4
	v_add_f32_e32 v6, v4, v8
	v_add_f32_e32 v7, v5, v9
	v_sub_f32_e32 v5, v100, v192
	v_add_f32_e32 v10, v6, v6
	v_add_f32_e32 v11, v6, v7
	v_sub_f32_e32 v6, v84, v192
	v_exp_f32_e32 v5, v5
	v_exp_f32_e32 v9, v6
	v_sub_f32_e32 v6, v101, v192
	v_sub_f32_e32 v7, v85, v192
	v_exp_f32_e32 v6, v6
	v_exp_f32_e32 v10, v7
	v_add_f32_e32 v7, v5, v9
	v_cvt_pk_bf16_f32 v198, v5, v6
	v_add_f32_e32 v12, v6, v10
	v_add_f32_e32 v13, v7, v11
	v_sub_f32_e32 v7, v102, v192
	v_add_f32_e32 v13, v12, v13
	v_add_f32_e32 v12, v12, v12
	v_sub_f32_e32 v11, v86, v192
	v_sub_f32_e32 v12, v103, v192
	v_exp_f32_e32 v7, v7
	v_exp_f32_e32 v11, v11
	v_exp_f32_e32 v14, v12
	v_sub_f32_e32 v12, v87, v192
	v_exp_f32_e32 v12, v12
	v_add_f32_e32 v15, v7, v11
	v_cvt_pk_bf16_f32 v199, v7, v14
	v_cvt_pk_bf16_f32 v200, v194, v0
	v_add_f32_e32 v80, v14, v12
	v_add_f32_e32 v81, v15, v13
	v_sub_f32_e32 v13, v104, v192
	v_add_f32_e32 v81, v80, v81
	v_add_f32_e32 v80, v80, v80
	v_sub_f32_e32 v15, v88, v192
	v_sub_f32_e32 v80, v105, v192
	v_exp_f32_e32 v13, v13
	v_exp_f32_e32 v15, v15
	v_exp_f32_e32 v82, v80
	v_sub_f32_e32 v80, v89, v192
	v_exp_f32_e32 v80, v80
	v_add_f32_e32 v83, v13, v15
	v_cvt_pk_bf16_f32 v201, v98, v8
	v_cvt_pk_bf16_f32 v202, v9, v10
	v_add_f32_e32 v84, v82, v80
	v_add_f32_e32 v85, v83, v81
	v_sub_f32_e32 v81, v106, v192
	v_add_f32_e32 v85, v84, v85
	v_add_f32_e32 v84, v84, v84
	v_sub_f32_e32 v83, v90, v192
	v_sub_f32_e32 v84, v107, v192
	v_exp_f32_e32 v81, v81
	v_exp_f32_e32 v83, v83
	v_exp_f32_e32 v86, v84
	v_sub_f32_e32 v84, v91, v192
	v_exp_f32_e32 v84, v84
	v_add_f32_e32 v87, v81, v83
	v_cvt_pk_bf16_f32 v203, v11, v12
	v_cvt_pk_bf16_f32 v204, v13, v82
	v_add_f32_e32 v88, v86, v84
	v_add_f32_e32 v89, v87, v85
	v_sub_f32_e32 v85, v108, v192
	v_add_f32_e32 v89, v88, v89
	v_add_f32_e32 v88, v88, v88
	v_sub_f32_e32 v87, v92, v192
	v_sub_f32_e32 v88, v109, v192
	v_exp_f32_e32 v85, v85
	v_exp_f32_e32 v87, v87
	v_exp_f32_e32 v90, v88
	v_sub_f32_e32 v88, v93, v192
	v_exp_f32_e32 v88, v88
	v_add_f32_e32 v91, v85, v87
	v_cvt_pk_bf16_f32 v205, v81, v86
	v_cvt_pk_bf16_f32 v206, v85, v90
	v_add_f32_e32 v92, v90, v88
	v_add_f32_e32 v93, v91, v89
	v_sub_f32_e32 v89, v110, v192
	v_add_f32_e32 v93, v92, v93
	v_add_f32_e32 v92, v92, v92
	v_sub_f32_e32 v91, v94, v192
	v_sub_f32_e32 v92, v111, v192
	v_exp_f32_e32 v89, v89
	v_exp_f32_e32 v91, v91
	v_exp_f32_e32 v94, v92
	v_sub_f32_e32 v92, v95, v192
	v_exp_f32_e32 v92, v92
	v_add_f32_e32 v95, v89, v91
	v_cvt_pk_bf16_f32 v207, v89, v94
	v_cvt_pk_bf16_f32 v208, v15, v80
	v_add_f32_e32 v96, v94, v92
	v_add_f32_e32 v97, v95, v93
	v_cvt_pk_bf16_f32 v209, v83, v84
	v_add_f32_e32 v93, v96, v97
	v_add_f32_e32 v162, v162, v93
	v_cvt_pk_bf16_f32 v210, v87, v88
	v_cvt_pk_bf16_f32 v211, v91, v92
	s_waitcnt vmcnt(0)
	s_branch .Lfx_h2_done

.Lfx_h2_done:
	s_barrier
	s_add_i32 s63, s63, 1
	s_add_i32 s41, s41, -1
	s_addk_i32 s62, 0x80
	s_xor_b32 s76, s76, 0x10200
	s_xor_b32 s77, s77, 0x10200
	s_mov_b64 s[80:81], s[78:79]
	s_cmp_eq_u32 s41, -1
	s_cbranch_scc0 .Lfx_body
	s_andn2_b64 vcc, exec, s[80:81]
	s_cbranch_vccnz .Lfx_tail_done
	s_add_i32 s64, s77, s51
	v_add_u32_e32 v10, s64, v183
	v_add_u32_e32 v11, s64, v184
	v_add_u32_e32 v12, s64, v185
	v_add_u32_e32 v13, s64, v186
	ds_read_b64_tr_b16 v[2:3], v10 offset:32768
	ds_read_b64_tr_b16 v[4:5], v10 offset:34816
	ds_read_b64_tr_b16 v[6:7], v10 offset:36864
	ds_read_b64_tr_b16 v[8:9], v10 offset:38912
	ds_read_b64_tr_b16 v[212:213], v10 offset:40960
	ds_read_b64_tr_b16 v[214:215], v10 offset:43008
	ds_read_b64_tr_b16 v[216:217], v10 offset:45056
	ds_read_b64_tr_b16 v[218:219], v10 offset:47104
	s_waitcnt lgkmcnt(6)
	v_mfma_f32_32x32x16_bf16 v[64:79], v[2:5], v[196:199], v[64:79]
	ds_read_b64_tr_b16 v[220:221], v11 offset:32768
	ds_read_b64_tr_b16 v[222:223], v11 offset:34816
	s_waitcnt lgkmcnt(6)
	v_mfma_f32_32x32x16_bf16 v[64:79], v[6:9], v[204:207], v[64:79]
	ds_read_b64_tr_b16 v[224:225], v11 offset:36864
	ds_read_b64_tr_b16 v[226:227], v11 offset:38912
	s_waitcnt lgkmcnt(6)
	v_mfma_f32_32x32x16_bf16 v[64:79], v[212:215], v[200:203], v[64:79]
	ds_read_b64_tr_b16 v[228:229], v11 offset:40960
	ds_read_b64_tr_b16 v[230:231], v11 offset:43008
	s_waitcnt lgkmcnt(6)
	v_mfma_f32_32x32x16_bf16 v[64:79], v[216:219], v[208:211], v[64:79]
	ds_read_b64_tr_b16 v[232:233], v11 offset:45056
	ds_read_b64_tr_b16 v[234:235], v11 offset:47104
	s_waitcnt lgkmcnt(6)
	v_mfma_f32_32x32x16_bf16 v[48:63], v[220:223], v[196:199], v[48:63]
	ds_read_b64_tr_b16 v[2:3], v12 offset:32768
	ds_read_b64_tr_b16 v[4:5], v12 offset:34816
	s_waitcnt lgkmcnt(6)
	v_mfma_f32_32x32x16_bf16 v[48:63], v[224:227], v[204:207], v[48:63]
	ds_read_b64_tr_b16 v[6:7], v12 offset:36864
	ds_read_b64_tr_b16 v[8:9], v12 offset:38912
	s_waitcnt lgkmcnt(6)
	v_mfma_f32_32x32x16_bf16 v[48:63], v[228:231], v[200:203], v[48:63]
	ds_read_b64_tr_b16 v[212:213], v12 offset:40960
	ds_read_b64_tr_b16 v[214:215], v12 offset:43008
	s_waitcnt lgkmcnt(6)
	v_mfma_f32_32x32x16_bf16 v[48:63], v[232:235], v[208:211], v[48:63]
	ds_read_b64_tr_b16 v[216:217], v12 offset:45056
	ds_read_b64_tr_b16 v[218:219], v12 offset:47104
	s_waitcnt lgkmcnt(6)
	v_mfma_f32_32x32x16_bf16 v[32:47], v[2:5], v[196:199], v[32:47]
	ds_read_b64_tr_b16 v[220:221], v13 offset:32768
	ds_read_b64_tr_b16 v[222:223], v13 offset:34816
	s_waitcnt lgkmcnt(6)
	v_mfma_f32_32x32x16_bf16 v[32:47], v[6:9], v[204:207], v[32:47]
	ds_read_b64_tr_b16 v[224:225], v13 offset:36864
	ds_read_b64_tr_b16 v[226:227], v13 offset:38912
	s_waitcnt lgkmcnt(6)
	v_mfma_f32_32x32x16_bf16 v[32:47], v[212:215], v[200:203], v[32:47]
	ds_read_b64_tr_b16 v[228:229], v13 offset:40960
	ds_read_b64_tr_b16 v[230:231], v13 offset:43008
	s_waitcnt lgkmcnt(6)
	v_mfma_f32_32x32x16_bf16 v[32:47], v[216:219], v[208:211], v[32:47]
	ds_read_b64_tr_b16 v[232:233], v13 offset:45056
	ds_read_b64_tr_b16 v[234:235], v13 offset:47104
	s_waitcnt lgkmcnt(6)
	v_mfma_f32_32x32x16_bf16 v[16:31], v[220:223], v[196:199], v[16:31]
	s_waitcnt lgkmcnt(4)
	v_mfma_f32_32x32x16_bf16 v[16:31], v[224:227], v[204:207], v[16:31]
	s_waitcnt lgkmcnt(2)
	v_mfma_f32_32x32x16_bf16 v[16:31], v[228:231], v[200:203], v[16:31]
	s_waitcnt lgkmcnt(0)
	v_mfma_f32_32x32x16_bf16 v[16:31], v[232:235], v[208:211], v[16:31]
.Lfx_tail_done:
	s_barrier
	s_cmp_lg_u32 s42, 0
	s_cbranch_scc1 .Lfx_aligned
	s_barrier
.Lfx_aligned:
	s_mov_b32 m0, s75
	s_branch .LBB0_561
